# combo15 with the hidconv thin phase requesting 11 source blocks (22 loads) per trip, 4 trips per wave instead of 11
# speedup vs baseline: 1.0081x; 1.0001x over previous
; #define GAS __attribute__((address_space(1)))
; __device__ __forceinline__ float bf_lo(unsigned w) { return __uint_as_float(w << 16); }
; __device__ __forceinline__ float bf_hi(unsigned w) { return __uint_as_float(w & 0xffff0000u); }
; __device__ __forceinline__ void phase_hidconv(LAS unsigned char* lds, const bf16_t* HIDb, unsigned char* HID8, const float* hmx, float* hrs, int grp, int rank, int wv) {
;     ...
;     for (int ui = wave; ui < 2 * 11 * 16; ui += 8) {
;         const int st8 = ui & 15, kk = (ui >> 4) % 11, h = (ui >> 4) / 11;
;         const int kt8 = mem * 11 + kk, rb = st8 >> 1, h2 = st8 & 1;
;         const GAS char* src = (const GAS char*)HIDb + ((size_t)(2 * pm + h) * KT_F + (2 * kt8 + h2)) * pg8::HTB + (size_t)(rb * 2048) + lane * 16;
;         GAS char* dst = (GAS char*)HID8 + ((size_t)(2 * pm + h) * KT_F8 + kt8) * pg8::HTB + (size_t)(st8 * 1024);
;         const u32x4 a = *(const GAS u32x4*)src, b = *(const GAS u32x4*)(src + 1024);
;         const float s_ = sc[h * 128 + rb * 16 + rr];
;         u32x2 wa, wb;
;         wa.x = cvt_i8x4(bf_lo(a.x) * s_, bf_hi(a.x) * s_, bf_lo(a.y) * s_, bf_hi(a.y) * s_); wa.y = cvt_i8x4(bf_lo(a.z) * s_, bf_hi(a.z) * s_, bf_lo(a.w) * s_, bf_hi(a.w) * s_);
;         wb.x = cvt_i8x4(bf_lo(b.x) * s_, bf_hi(b.x) * s_, bf_lo(b.y) * s_, bf_hi(b.y) * s_); wb.y = cvt_i8x4(bf_lo(b.z) * s_, bf_hi(b.z) * s_, bf_lo(b.w) * s_, bf_hi(b.w) * s_);
;         *(GAS u32x2*)(dst + d0) = wa; *(GAS u32x2*)(dst + d1) = wb;
.LBB0_573:
	s_ashr_i32 s4, s0, 4
	s_mul_hi_i32 s5, s4, 0x2e8ba2e9
	s_lshr_b32 s7, s5, 31
	s_ashr_i32 s5, s5, 1
	s_add_i32 s7, s5, s7
	s_mul_i32 s5, s7, 11
	s_sub_i32 s4, s4, s5
	s_mul_i32 s5, s66, 11
	s_add_i32 s8, s4, s5
	s_lshl_b32 s11, s8, 1
	s_add_i32 s10, s7, s13
	s_or_b32 s11, s11, s3
	s_and_b32 s6, s0, 15
	s_bfe_u32 s9, s0, 0x30001
	s_mul_i32 s4, s10, 0x58
	s_ashr_i32 s12, s11, 31
	s_mul_hi_i32 s5, s10, 0x58
	s_add_u32 s4, s4, s11
	s_addc_u32 s5, s5, s12
	s_lshl_b64 s[4:5], s[4:5], 14
	s_add_u32 s4, s64, s4
	s_addc_u32 s5, s65, s5
	s_lshl_b32 s11, s9, 11
	s_add_u32 s4, s4, s11
	s_addc_u32 s5, s5, 0
	v_lshl_add_u64 v[12:13], s[4:5], 0, v[0:1]
	global_load_dwordx4 v[64:67], v[12:13], off
	s_nop 0
	global_load_dwordx4 v[68:71], v[12:13], off offset:1024
	s_add_i32 s0, s0, 8
	s_ashr_i32 s4, s0, 4
	s_mul_hi_i32 s5, s4, 0x2e8ba2e9
	s_lshr_b32 s7, s5, 31
	s_ashr_i32 s5, s5, 1
	s_add_i32 s7, s5, s7
	s_mul_i32 s5, s7, 11
	s_sub_i32 s4, s4, s5
	s_mul_i32 s5, s66, 11
	s_add_i32 s8, s4, s5
	s_lshl_b32 s11, s8, 1
	s_add_i32 s10, s7, s13
	s_or_b32 s11, s11, s3
	s_and_b32 s6, s0, 15
	s_bfe_u32 s9, s0, 0x30001
	s_mul_i32 s4, s10, 0x58
	s_ashr_i32 s12, s11, 31
	s_mul_hi_i32 s5, s10, 0x58
	s_add_u32 s4, s4, s11
	s_addc_u32 s5, s5, s12
	s_lshl_b64 s[4:5], s[4:5], 14
	s_add_u32 s4, s64, s4
	s_addc_u32 s5, s65, s5
	s_lshl_b32 s11, s9, 11
	s_add_u32 s4, s4, s11
	s_addc_u32 s5, s5, 0
	v_lshl_add_u64 v[12:13], s[4:5], 0, v[0:1]
	global_load_dwordx4 v[72:75], v[12:13], off
	s_nop 0
	global_load_dwordx4 v[76:79], v[12:13], off offset:1024
	s_add_i32 s0, s0, 8
	s_ashr_i32 s4, s0, 4
	s_mul_hi_i32 s5, s4, 0x2e8ba2e9
	s_lshr_b32 s7, s5, 31
	s_ashr_i32 s5, s5, 1
	s_add_i32 s7, s5, s7
	s_mul_i32 s5, s7, 11
	s_sub_i32 s4, s4, s5
	s_mul_i32 s5, s66, 11
	s_add_i32 s8, s4, s5
	s_lshl_b32 s11, s8, 1
	s_add_i32 s10, s7, s13
	s_or_b32 s11, s11, s3
	s_and_b32 s6, s0, 15
	s_bfe_u32 s9, s0, 0x30001
	s_mul_i32 s4, s10, 0x58
	s_ashr_i32 s12, s11, 31
	s_mul_hi_i32 s5, s10, 0x58
	s_add_u32 s4, s4, s11
	s_addc_u32 s5, s5, s12
	s_lshl_b64 s[4:5], s[4:5], 14
	s_add_u32 s4, s64, s4
	s_addc_u32 s5, s65, s5
	s_lshl_b32 s11, s9, 11
	s_add_u32 s4, s4, s11
	s_addc_u32 s5, s5, 0
	v_lshl_add_u64 v[12:13], s[4:5], 0, v[0:1]
	global_load_dwordx4 v[80:83], v[12:13], off
	s_nop 0
	global_load_dwordx4 v[84:87], v[12:13], off offset:1024
	s_add_i32 s0, s0, 8
	s_ashr_i32 s4, s0, 4
	s_mul_hi_i32 s5, s4, 0x2e8ba2e9
	s_lshr_b32 s7, s5, 31
	s_ashr_i32 s5, s5, 1
	s_add_i32 s7, s5, s7
	s_mul_i32 s5, s7, 11
	s_sub_i32 s4, s4, s5
	s_mul_i32 s5, s66, 11
	s_add_i32 s8, s4, s5
	s_lshl_b32 s11, s8, 1
	s_add_i32 s10, s7, s13
	s_or_b32 s11, s11, s3
	s_and_b32 s6, s0, 15
	s_bfe_u32 s9, s0, 0x30001
	s_mul_i32 s4, s10, 0x58
	s_ashr_i32 s12, s11, 31
	s_mul_hi_i32 s5, s10, 0x58
	s_add_u32 s4, s4, s11
	s_addc_u32 s5, s5, s12
	s_lshl_b64 s[4:5], s[4:5], 14
	s_add_u32 s4, s64, s4
	s_addc_u32 s5, s65, s5
	s_lshl_b32 s11, s9, 11
	s_add_u32 s4, s4, s11
	s_addc_u32 s5, s5, 0
	v_lshl_add_u64 v[12:13], s[4:5], 0, v[0:1]
	global_load_dwordx4 v[88:91], v[12:13], off
	s_nop 0
	global_load_dwordx4 v[92:95], v[12:13], off offset:1024
	s_add_i32 s0, s0, 8
	s_ashr_i32 s4, s0, 4
	s_mul_hi_i32 s5, s4, 0x2e8ba2e9
	s_lshr_b32 s7, s5, 31
	s_ashr_i32 s5, s5, 1
	s_add_i32 s7, s5, s7
	s_mul_i32 s5, s7, 11
	s_sub_i32 s4, s4, s5
	s_mul_i32 s5, s66, 11
	s_add_i32 s8, s4, s5
	s_lshl_b32 s11, s8, 1
	s_add_i32 s10, s7, s13
	s_or_b32 s11, s11, s3
	s_and_b32 s6, s0, 15
	s_bfe_u32 s9, s0, 0x30001
	s_mul_i32 s4, s10, 0x58
	s_ashr_i32 s12, s11, 31
	s_mul_hi_i32 s5, s10, 0x58
	s_add_u32 s4, s4, s11
	s_addc_u32 s5, s5, s12
	s_lshl_b64 s[4:5], s[4:5], 14
	s_add_u32 s4, s64, s4
	s_addc_u32 s5, s65, s5
	s_lshl_b32 s11, s9, 11
	s_add_u32 s4, s4, s11
	s_addc_u32 s5, s5, 0
	v_lshl_add_u64 v[12:13], s[4:5], 0, v[0:1]
	global_load_dwordx4 v[96:99], v[12:13], off
	s_nop 0
	global_load_dwordx4 v[100:103], v[12:13], off offset:1024
	s_add_i32 s0, s0, 8
	s_ashr_i32 s4, s0, 4
	s_mul_hi_i32 s5, s4, 0x2e8ba2e9
	s_lshr_b32 s7, s5, 31
	s_ashr_i32 s5, s5, 1
	s_add_i32 s7, s5, s7
	s_mul_i32 s5, s7, 11
	s_sub_i32 s4, s4, s5
	s_mul_i32 s5, s66, 11
	s_add_i32 s8, s4, s5
	s_lshl_b32 s11, s8, 1
	s_add_i32 s10, s7, s13
	s_or_b32 s11, s11, s3
	s_and_b32 s6, s0, 15
	s_bfe_u32 s9, s0, 0x30001
	s_mul_i32 s4, s10, 0x58
	s_ashr_i32 s12, s11, 31
	s_mul_hi_i32 s5, s10, 0x58
	s_add_u32 s4, s4, s11
	s_addc_u32 s5, s5, s12
	s_lshl_b64 s[4:5], s[4:5], 14
	s_add_u32 s4, s64, s4
	s_addc_u32 s5, s65, s5
	s_lshl_b32 s11, s9, 11
	s_add_u32 s4, s4, s11
	s_addc_u32 s5, s5, 0
	v_lshl_add_u64 v[12:13], s[4:5], 0, v[0:1]
	global_load_dwordx4 v[104:107], v[12:13], off
	s_nop 0
	global_load_dwordx4 v[108:111], v[12:13], off offset:1024
	s_add_i32 s0, s0, 8
	s_ashr_i32 s4, s0, 4
	s_mul_hi_i32 s5, s4, 0x2e8ba2e9
	s_lshr_b32 s7, s5, 31
	s_ashr_i32 s5, s5, 1
	s_add_i32 s7, s5, s7
	s_mul_i32 s5, s7, 11
	s_sub_i32 s4, s4, s5
	s_mul_i32 s5, s66, 11
	s_add_i32 s8, s4, s5
	s_lshl_b32 s11, s8, 1
	s_add_i32 s10, s7, s13
	s_or_b32 s11, s11, s3
	s_and_b32 s6, s0, 15
	s_bfe_u32 s9, s0, 0x30001
	s_mul_i32 s4, s10, 0x58
	s_ashr_i32 s12, s11, 31
	s_mul_hi_i32 s5, s10, 0x58
	s_add_u32 s4, s4, s11
	s_addc_u32 s5, s5, s12
	s_lshl_b64 s[4:5], s[4:5], 14
	s_add_u32 s4, s64, s4
	s_addc_u32 s5, s65, s5
	s_lshl_b32 s11, s9, 11
	s_add_u32 s4, s4, s11
	s_addc_u32 s5, s5, 0
	v_lshl_add_u64 v[12:13], s[4:5], 0, v[0:1]
	global_load_dwordx4 v[112:115], v[12:13], off
	s_nop 0
	global_load_dwordx4 v[116:119], v[12:13], off offset:1024
	s_add_i32 s0, s0, 8
	s_ashr_i32 s4, s0, 4
	s_mul_hi_i32 s5, s4, 0x2e8ba2e9
	s_lshr_b32 s7, s5, 31
	s_ashr_i32 s5, s5, 1
	s_add_i32 s7, s5, s7
	s_mul_i32 s5, s7, 11
	s_sub_i32 s4, s4, s5
; #define GAS __attribute__((address_space(1)))
; __device__ __forceinline__ float bf_lo(unsigned w) { return __uint_as_float(w << 16); }
; __device__ __forceinline__ float bf_hi(unsigned w) { return __uint_as_float(w & 0xffff0000u); }
; __device__ __forceinline__ void phase_hidconv(LAS unsigned char* lds, const bf16_t* HIDb, unsigned char* HID8, const float* hmx, float* hrs, int grp, int rank, int wv) {
;     ...
;     for (int ui = wave; ui < 2 * 11 * 16; ui += 8) {
;         const int st8 = ui & 15, kk = (ui >> 4) % 11, h = (ui >> 4) / 11;
;         const int kt8 = mem * 11 + kk, rb = st8 >> 1, h2 = st8 & 1;
;         const GAS char* src = (const GAS char*)HIDb + ((size_t)(2 * pm + h) * KT_F + (2 * kt8 + h2)) * pg8::HTB + (size_t)(rb * 2048) + lane * 16;
;         GAS char* dst = (GAS char*)HID8 + ((size_t)(2 * pm + h) * KT_F8 + kt8) * pg8::HTB + (size_t)(st8 * 1024);
;         const u32x4 a = *(const GAS u32x4*)src, b = *(const GAS u32x4*)(src + 1024);
;         const float s_ = sc[h * 128 + rb * 16 + rr];
;         u32x2 wa, wb;
;         wa.x = cvt_i8x4(bf_lo(a.x) * s_, bf_hi(a.x) * s_, bf_lo(a.y) * s_, bf_hi(a.y) * s_); wa.y = cvt_i8x4(bf_lo(a.z) * s_, bf_hi(a.z) * s_, bf_lo(a.w) * s_, bf_hi(a.w) * s_);
;         wb.x = cvt_i8x4(bf_lo(b.x) * s_, bf_hi(b.x) * s_, bf_lo(b.y) * s_, bf_hi(b.y) * s_); wb.y = cvt_i8x4(bf_lo(b.z) * s_, bf_hi(b.z) * s_, bf_lo(b.w) * s_, bf_hi(b.w) * s_);
;         *(GAS u32x2*)(dst + d0) = wa; *(GAS u32x2*)(dst + d1) = wb;
	s_mul_i32 s5, s66, 11
	s_add_i32 s8, s4, s5
	s_lshl_b32 s11, s8, 1
	s_add_i32 s10, s7, s13
	s_or_b32 s11, s11, s3
	s_and_b32 s6, s0, 15
	s_bfe_u32 s9, s0, 0x30001
	s_mul_i32 s4, s10, 0x58
	s_ashr_i32 s12, s11, 31
	s_mul_hi_i32 s5, s10, 0x58
	s_add_u32 s4, s4, s11
	s_addc_u32 s5, s5, s12
	s_lshl_b64 s[4:5], s[4:5], 14
	s_add_u32 s4, s64, s4
	s_addc_u32 s5, s65, s5
	s_lshl_b32 s11, s9, 11
	s_add_u32 s4, s4, s11
	s_addc_u32 s5, s5, 0
	v_lshl_add_u64 v[12:13], s[4:5], 0, v[0:1]
	global_load_dwordx4 v[120:123], v[12:13], off
	s_nop 0
	global_load_dwordx4 v[124:127], v[12:13], off offset:1024
	s_add_i32 s0, s0, 8
	s_ashr_i32 s4, s0, 4
	s_mul_hi_i32 s5, s4, 0x2e8ba2e9
	s_lshr_b32 s7, s5, 31
	s_ashr_i32 s5, s5, 1
	s_add_i32 s7, s5, s7
	s_mul_i32 s5, s7, 11
	s_sub_i32 s4, s4, s5
	s_mul_i32 s5, s66, 11
	s_add_i32 s8, s4, s5
	s_lshl_b32 s11, s8, 1
	s_add_i32 s10, s7, s13
	s_or_b32 s11, s11, s3
	s_and_b32 s6, s0, 15
	s_bfe_u32 s9, s0, 0x30001
	s_mul_i32 s4, s10, 0x58
	s_ashr_i32 s12, s11, 31
	s_mul_hi_i32 s5, s10, 0x58
	s_add_u32 s4, s4, s11
	s_addc_u32 s5, s5, s12
	s_lshl_b64 s[4:5], s[4:5], 14
	s_add_u32 s4, s64, s4
	s_addc_u32 s5, s65, s5
	s_lshl_b32 s11, s9, 11
	s_add_u32 s4, s4, s11
	s_addc_u32 s5, s5, 0
	v_lshl_add_u64 v[12:13], s[4:5], 0, v[0:1]
	global_load_dwordx4 v[128:131], v[12:13], off
	s_nop 0
	global_load_dwordx4 v[132:135], v[12:13], off offset:1024
	s_add_i32 s0, s0, 8
	s_ashr_i32 s4, s0, 4
	s_mul_hi_i32 s5, s4, 0x2e8ba2e9
	s_lshr_b32 s7, s5, 31
	s_ashr_i32 s5, s5, 1
	s_add_i32 s7, s5, s7
	s_mul_i32 s5, s7, 11
	s_sub_i32 s4, s4, s5
	s_mul_i32 s5, s66, 11
	s_add_i32 s8, s4, s5
	s_lshl_b32 s11, s8, 1
	s_add_i32 s10, s7, s13
	s_or_b32 s11, s11, s3
	s_and_b32 s6, s0, 15
	s_bfe_u32 s9, s0, 0x30001
	s_mul_i32 s4, s10, 0x58
	s_ashr_i32 s12, s11, 31
	s_mul_hi_i32 s5, s10, 0x58
	s_add_u32 s4, s4, s11
	s_addc_u32 s5, s5, s12
	s_lshl_b64 s[4:5], s[4:5], 14
	s_add_u32 s4, s64, s4
	s_addc_u32 s5, s65, s5
	s_lshl_b32 s11, s9, 11
	s_add_u32 s4, s4, s11
	s_addc_u32 s5, s5, 0
	v_lshl_add_u64 v[12:13], s[4:5], 0, v[0:1]
	global_load_dwordx4 v[136:139], v[12:13], off
	s_nop 0
	global_load_dwordx4 v[140:143], v[12:13], off offset:1024
	s_add_i32 s0, s0, 8
	s_ashr_i32 s4, s0, 4
	s_mul_hi_i32 s5, s4, 0x2e8ba2e9
	s_lshr_b32 s7, s5, 31
	s_ashr_i32 s5, s5, 1
	s_add_i32 s7, s5, s7
	s_mul_i32 s5, s7, 11
	s_sub_i32 s4, s4, s5
	s_mul_i32 s5, s66, 11
	s_add_i32 s8, s4, s5
	s_lshl_b32 s11, s8, 1
	s_add_i32 s10, s7, s13
	s_or_b32 s11, s11, s3
	s_and_b32 s6, s0, 15
	s_bfe_u32 s9, s0, 0x30001
	s_mul_i32 s4, s10, 0x58
	s_ashr_i32 s12, s11, 31
	s_mul_hi_i32 s5, s10, 0x58
	s_add_u32 s4, s4, s11
	s_addc_u32 s5, s5, s12
	s_lshl_b64 s[4:5], s[4:5], 14
	s_add_u32 s4, s64, s4
	s_addc_u32 s5, s65, s5
	s_lshl_b32 s11, s9, 11
	s_add_u32 s4, s4, s11
	s_addc_u32 s5, s5, 0
	v_lshl_add_u64 v[12:13], s[4:5], 0, v[0:1]
	global_load_dwordx4 v[144:147], v[12:13], off
	s_nop 0
	global_load_dwordx4 v[148:151], v[12:13], off offset:1024
	s_sub_i32 s0, s0, 80
	s_ashr_i32 s4, s0, 4
	s_mul_hi_i32 s5, s4, 0x2e8ba2e9
	s_lshr_b32 s7, s5, 31
	s_ashr_i32 s5, s5, 1
	s_add_i32 s7, s5, s7
	s_mul_i32 s5, s7, 11
	s_sub_i32 s4, s4, s5
	s_mul_i32 s5, s66, 11
	s_add_i32 s8, s4, s5
	s_lshl_b32 s11, s8, 1
	s_add_i32 s10, s7, s13
	s_or_b32 s11, s11, s3
	s_and_b32 s6, s0, 15
	s_bfe_u32 s9, s0, 0x30001
	s_waitcnt vmcnt(20)
	v_mov_b32_e32 v8, v64
	v_mov_b32_e32 v9, v65
	v_mov_b32_e32 v10, v66
	v_mov_b32_e32 v11, v67
	v_mov_b32_e32 v12, v68
	v_mov_b32_e32 v13, v69
	v_mov_b32_e32 v14, v70
	v_mov_b32_e32 v15, v71
	s_mul_hi_i32 s5, s10, 44
	s_mul_i32 s10, s10, 44
	s_ashr_i32 s11, s8, 31
	s_add_u32 s4, s10, s8
	s_addc_u32 s5, s5, s11
	s_lshl_b64 s[4:5], s[4:5], 14
	s_add_u32 s4, s1, s4
	s_addc_u32 s5, s2, s5
	s_lshl_b32 s6, s6, 10
	s_add_u32 s4, s4, s6
	s_addc_u32 s5, s5, 0
	s_lshl_b32 s6, s7, 9
	s_add_i32 s6, s40, s6
	s_lshl_b32 s7, s9, 6
	s_add_i32 s6, s6, s7
	v_lshl_add_u32 v7, v6, 2, s6
	ds_read_b32 v7, v7
	v_lshlrev_b32_e32 v16, 16, v8
	v_and_b32_e32 v8, 0xffff0000, v8
	s_waitcnt lgkmcnt(0)
	v_fmaak_f32 v16, v7, v16, 0x43000000
	v_lshlrev_b32_e32 v17, 16, v9
	v_cvt_pk_u8_f32 v16, v16, 0, 0
	v_fmaak_f32 v8, v7, v8, 0x43000000
	v_and_b32_e32 v9, 0xffff0000, v9
	v_cvt_pk_u8_f32 v8, v8, 1, v16
	v_fmaak_f32 v16, v7, v17, 0x43000000
	v_cvt_pk_u8_f32 v8, v16, 2, v8
	v_fmaak_f32 v9, v7, v9, 0x43000000
	v_cvt_pk_u8_f32 v8, v9, 3, v8
	v_lshlrev_b32_e32 v9, 16, v10
	v_and_b32_e32 v10, 0xffff0000, v10
	v_fmaak_f32 v9, v7, v9, 0x43000000
	v_lshlrev_b32_e32 v16, 16, v11
	v_cvt_pk_u8_f32 v9, v9, 0, 0
	v_fmaak_f32 v10, v7, v10, 0x43000000
	v_and_b32_e32 v11, 0xffff0000, v11
	v_cvt_pk_u8_f32 v9, v10, 1, v9
	v_fmaak_f32 v10, v7, v16, 0x43000000
	v_cvt_pk_u8_f32 v9, v10, 2, v9
	v_fmaak_f32 v10, v7, v11, 0x43000000
	v_cvt_pk_u8_f32 v9, v10, 3, v9
	v_lshlrev_b32_e32 v10, 16, v12
	v_and_b32_e32 v11, 0xffff0000, v12
	v_fmaak_f32 v10, v7, v10, 0x43000000
	v_lshlrev_b32_e32 v12, 16, v13
	v_cvt_pk_u8_f32 v10, v10, 0, 0
	v_fmaak_f32 v11, v7, v11, 0x43000000
	v_and_b32_e32 v13, 0xffff0000, v13
	v_cvt_pk_u8_f32 v10, v11, 1, v10
	v_fmaak_f32 v11, v7, v12, 0x43000000
	v_cvt_pk_u8_f32 v10, v11, 2, v10
	v_fmaak_f32 v11, v7, v13, 0x43000000
	v_cvt_pk_u8_f32 v10, v11, 3, v10
	v_lshlrev_b32_e32 v11, 16, v14
	v_and_b32_e32 v12, 0xffff0000, v14
	v_fmaak_f32 v11, v7, v11, 0x43000000
	v_lshlrev_b32_e32 v13, 16, v15
	v_cvt_pk_u8_f32 v11, v11, 0, 0
	v_fmaak_f32 v12, v7, v12, 0x43000000
	v_and_b32_e32 v14, 0xffff0000, v15
	v_cvt_pk_u8_f32 v11, v12, 1, v11
	v_fmaak_f32 v12, v7, v13, 0x43000000
	v_xor_b32_e32 v8, 0x80808080, v8
	v_xor_b32_e32 v9, 0x80808080, v9
	v_cvt_pk_u8_f32 v11, v12, 2, v11
	v_fmaak_f32 v7, v7, v14, 0x43000000
	v_lshl_add_u64 v[12:13], s[4:5], 0, v[4:5]
	v_cvt_pk_u8_f32 v7, v7, 3, v11
	global_store_dwordx2 v[12:13], v[8:9], off
	v_lshl_add_u64 v[8:9], s[4:5], 0, v[2:3]
	v_xor_b32_e32 v10, 0x80808080, v10
	v_xor_b32_e32 v11, 0x80808080, v7
	global_store_dwordx2 v[8:9], v[10:11], off
	s_add_i32 s0, s0, 8
	s_ashr_i32 s4, s0, 4
	s_mul_hi_i32 s5, s4, 0x2e8ba2e9
	s_lshr_b32 s7, s5, 31
	s_ashr_i32 s5, s5, 1
	s_add_i32 s7, s5, s7
	s_mul_i32 s5, s7, 11
	s_sub_i32 s4, s4, s5
	s_mul_i32 s5, s66, 11
	s_add_i32 s8, s4, s5
	s_lshl_b32 s11, s8, 1
	s_add_i32 s10, s7, s13
	s_or_b32 s11, s11, s3
	s_and_b32 s6, s0, 15
	s_bfe_u32 s9, s0, 0x30001
	s_waitcnt vmcnt(20)
; #define GAS __attribute__((address_space(1)))
; __device__ __forceinline__ float bf_lo(unsigned w) { return __uint_as_float(w << 16); }
; __device__ __forceinline__ float bf_hi(unsigned w) { return __uint_as_float(w & 0xffff0000u); }
; __device__ __forceinline__ void phase_hidconv(LAS unsigned char* lds, const bf16_t* HIDb, unsigned char* HID8, const float* hmx, float* hrs, int grp, int rank, int wv) {
;     ...
;     for (int ui = wave; ui < 2 * 11 * 16; ui += 8) {
;         const int st8 = ui & 15, kk = (ui >> 4) % 11, h = (ui >> 4) / 11;
;         const int kt8 = mem * 11 + kk, rb = st8 >> 1, h2 = st8 & 1;
;         const GAS char* src = (const GAS char*)HIDb + ((size_t)(2 * pm + h) * KT_F + (2 * kt8 + h2)) * pg8::HTB + (size_t)(rb * 2048) + lane * 16;
;         GAS char* dst = (GAS char*)HID8 + ((size_t)(2 * pm + h) * KT_F8 + kt8) * pg8::HTB + (size_t)(st8 * 1024);
;         const u32x4 a = *(const GAS u32x4*)src, b = *(const GAS u32x4*)(src + 1024);
;         const float s_ = sc[h * 128 + rb * 16 + rr];
;         u32x2 wa, wb;
;         wa.x = cvt_i8x4(bf_lo(a.x) * s_, bf_hi(a.x) * s_, bf_lo(a.y) * s_, bf_hi(a.y) * s_); wa.y = cvt_i8x4(bf_lo(a.z) * s_, bf_hi(a.z) * s_, bf_lo(a.w) * s_, bf_hi(a.w) * s_);
;         wb.x = cvt_i8x4(bf_lo(b.x) * s_, bf_hi(b.x) * s_, bf_lo(b.y) * s_, bf_hi(b.y) * s_); wb.y = cvt_i8x4(bf_lo(b.z) * s_, bf_hi(b.z) * s_, bf_lo(b.w) * s_, bf_hi(b.w) * s_);
;         *(GAS u32x2*)(dst + d0) = wa; *(GAS u32x2*)(dst + d1) = wb;
	v_mov_b32_e32 v8, v72
	v_mov_b32_e32 v9, v73
	v_mov_b32_e32 v10, v74
	v_mov_b32_e32 v11, v75
	v_mov_b32_e32 v12, v76
	v_mov_b32_e32 v13, v77
	v_mov_b32_e32 v14, v78
	v_mov_b32_e32 v15, v79
	s_mul_hi_i32 s5, s10, 44
	s_mul_i32 s10, s10, 44
	s_ashr_i32 s11, s8, 31
	s_add_u32 s4, s10, s8
	s_addc_u32 s5, s5, s11
	s_lshl_b64 s[4:5], s[4:5], 14
	s_add_u32 s4, s1, s4
	s_addc_u32 s5, s2, s5
	s_lshl_b32 s6, s6, 10
	s_add_u32 s4, s4, s6
	s_addc_u32 s5, s5, 0
	s_lshl_b32 s6, s7, 9
	s_add_i32 s6, s40, s6
	s_lshl_b32 s7, s9, 6
	s_add_i32 s6, s6, s7
	v_lshl_add_u32 v7, v6, 2, s6
	ds_read_b32 v7, v7
	v_lshlrev_b32_e32 v16, 16, v8
	v_and_b32_e32 v8, 0xffff0000, v8
	s_waitcnt lgkmcnt(0)
	v_fmaak_f32 v16, v7, v16, 0x43000000
	v_lshlrev_b32_e32 v17, 16, v9
	v_cvt_pk_u8_f32 v16, v16, 0, 0
	v_fmaak_f32 v8, v7, v8, 0x43000000
	v_and_b32_e32 v9, 0xffff0000, v9
	v_cvt_pk_u8_f32 v8, v8, 1, v16
	v_fmaak_f32 v16, v7, v17, 0x43000000
	v_cvt_pk_u8_f32 v8, v16, 2, v8
	v_fmaak_f32 v9, v7, v9, 0x43000000
	v_cvt_pk_u8_f32 v8, v9, 3, v8
	v_lshlrev_b32_e32 v9, 16, v10
	v_and_b32_e32 v10, 0xffff0000, v10
	v_fmaak_f32 v9, v7, v9, 0x43000000
	v_lshlrev_b32_e32 v16, 16, v11
	v_cvt_pk_u8_f32 v9, v9, 0, 0
	v_fmaak_f32 v10, v7, v10, 0x43000000
	v_and_b32_e32 v11, 0xffff0000, v11
	v_cvt_pk_u8_f32 v9, v10, 1, v9
	v_fmaak_f32 v10, v7, v16, 0x43000000
	v_cvt_pk_u8_f32 v9, v10, 2, v9
	v_fmaak_f32 v10, v7, v11, 0x43000000
	v_cvt_pk_u8_f32 v9, v10, 3, v9
	v_lshlrev_b32_e32 v10, 16, v12
	v_and_b32_e32 v11, 0xffff0000, v12
	v_fmaak_f32 v10, v7, v10, 0x43000000
	v_lshlrev_b32_e32 v12, 16, v13
	v_cvt_pk_u8_f32 v10, v10, 0, 0
	v_fmaak_f32 v11, v7, v11, 0x43000000
	v_and_b32_e32 v13, 0xffff0000, v13
	v_cvt_pk_u8_f32 v10, v11, 1, v10
	v_fmaak_f32 v11, v7, v12, 0x43000000
	v_cvt_pk_u8_f32 v10, v11, 2, v10
	v_fmaak_f32 v11, v7, v13, 0x43000000
	v_cvt_pk_u8_f32 v10, v11, 3, v10
	v_lshlrev_b32_e32 v11, 16, v14
	v_and_b32_e32 v12, 0xffff0000, v14
	v_fmaak_f32 v11, v7, v11, 0x43000000
	v_lshlrev_b32_e32 v13, 16, v15
	v_cvt_pk_u8_f32 v11, v11, 0, 0
	v_fmaak_f32 v12, v7, v12, 0x43000000
	v_and_b32_e32 v14, 0xffff0000, v15
	v_cvt_pk_u8_f32 v11, v12, 1, v11
	v_fmaak_f32 v12, v7, v13, 0x43000000
	v_xor_b32_e32 v8, 0x80808080, v8
	v_xor_b32_e32 v9, 0x80808080, v9
	v_cvt_pk_u8_f32 v11, v12, 2, v11
	v_fmaak_f32 v7, v7, v14, 0x43000000
	v_lshl_add_u64 v[12:13], s[4:5], 0, v[4:5]
	v_cvt_pk_u8_f32 v7, v7, 3, v11
	global_store_dwordx2 v[12:13], v[8:9], off
	v_lshl_add_u64 v[8:9], s[4:5], 0, v[2:3]
	v_xor_b32_e32 v10, 0x80808080, v10
	v_xor_b32_e32 v11, 0x80808080, v7
	global_store_dwordx2 v[8:9], v[10:11], off
	s_add_i32 s0, s0, 8
	s_ashr_i32 s4, s0, 4
	s_mul_hi_i32 s5, s4, 0x2e8ba2e9
	s_lshr_b32 s7, s5, 31
	s_ashr_i32 s5, s5, 1
	s_add_i32 s7, s5, s7
	s_mul_i32 s5, s7, 11
	s_sub_i32 s4, s4, s5
	s_mul_i32 s5, s66, 11
	s_add_i32 s8, s4, s5
	s_lshl_b32 s11, s8, 1
	s_add_i32 s10, s7, s13
	s_or_b32 s11, s11, s3
	s_and_b32 s6, s0, 15
	s_bfe_u32 s9, s0, 0x30001
	s_waitcnt vmcnt(20)
	v_mov_b32_e32 v8, v80
	v_mov_b32_e32 v9, v81
	v_mov_b32_e32 v10, v82
	v_mov_b32_e32 v11, v83
	v_mov_b32_e32 v12, v84
	v_mov_b32_e32 v13, v85
	v_mov_b32_e32 v14, v86
	v_mov_b32_e32 v15, v87
	s_mul_hi_i32 s5, s10, 44
	s_mul_i32 s10, s10, 44
	s_ashr_i32 s11, s8, 31
	s_add_u32 s4, s10, s8
	s_addc_u32 s5, s5, s11
	s_lshl_b64 s[4:5], s[4:5], 14
	s_add_u32 s4, s1, s4
	s_addc_u32 s5, s2, s5
	s_lshl_b32 s6, s6, 10
	s_add_u32 s4, s4, s6
	s_addc_u32 s5, s5, 0
	s_lshl_b32 s6, s7, 9
	s_add_i32 s6, s40, s6
	s_lshl_b32 s7, s9, 6
	s_add_i32 s6, s6, s7
	v_lshl_add_u32 v7, v6, 2, s6
	ds_read_b32 v7, v7
	v_lshlrev_b32_e32 v16, 16, v8
	v_and_b32_e32 v8, 0xffff0000, v8
	s_waitcnt lgkmcnt(0)
	v_fmaak_f32 v16, v7, v16, 0x43000000
	v_lshlrev_b32_e32 v17, 16, v9
	v_cvt_pk_u8_f32 v16, v16, 0, 0
	v_fmaak_f32 v8, v7, v8, 0x43000000
	v_and_b32_e32 v9, 0xffff0000, v9
	v_cvt_pk_u8_f32 v8, v8, 1, v16
	v_fmaak_f32 v16, v7, v17, 0x43000000
	v_cvt_pk_u8_f32 v8, v16, 2, v8
	v_fmaak_f32 v9, v7, v9, 0x43000000
	v_cvt_pk_u8_f32 v8, v9, 3, v8
	v_lshlrev_b32_e32 v9, 16, v10
	v_and_b32_e32 v10, 0xffff0000, v10
	v_fmaak_f32 v9, v7, v9, 0x43000000
	v_lshlrev_b32_e32 v16, 16, v11
	v_cvt_pk_u8_f32 v9, v9, 0, 0
	v_fmaak_f32 v10, v7, v10, 0x43000000
	v_and_b32_e32 v11, 0xffff0000, v11
	v_cvt_pk_u8_f32 v9, v10, 1, v9
	v_fmaak_f32 v10, v7, v16, 0x43000000
	v_cvt_pk_u8_f32 v9, v10, 2, v9
	v_fmaak_f32 v10, v7, v11, 0x43000000
	v_cvt_pk_u8_f32 v9, v10, 3, v9
	v_lshlrev_b32_e32 v10, 16, v12
	v_and_b32_e32 v11, 0xffff0000, v12
	v_fmaak_f32 v10, v7, v10, 0x43000000
	v_lshlrev_b32_e32 v12, 16, v13
	v_cvt_pk_u8_f32 v10, v10, 0, 0
	v_fmaak_f32 v11, v7, v11, 0x43000000
	v_and_b32_e32 v13, 0xffff0000, v13
	v_cvt_pk_u8_f32 v10, v11, 1, v10
	v_fmaak_f32 v11, v7, v12, 0x43000000
	v_cvt_pk_u8_f32 v10, v11, 2, v10
	v_fmaak_f32 v11, v7, v13, 0x43000000
	v_cvt_pk_u8_f32 v10, v11, 3, v10
	v_lshlrev_b32_e32 v11, 16, v14
	v_and_b32_e32 v12, 0xffff0000, v14
	v_fmaak_f32 v11, v7, v11, 0x43000000
	v_lshlrev_b32_e32 v13, 16, v15
	v_cvt_pk_u8_f32 v11, v11, 0, 0
	v_fmaak_f32 v12, v7, v12, 0x43000000
	v_and_b32_e32 v14, 0xffff0000, v15
	v_cvt_pk_u8_f32 v11, v12, 1, v11
	v_fmaak_f32 v12, v7, v13, 0x43000000
	v_xor_b32_e32 v8, 0x80808080, v8
	v_xor_b32_e32 v9, 0x80808080, v9
	v_cvt_pk_u8_f32 v11, v12, 2, v11
	v_fmaak_f32 v7, v7, v14, 0x43000000
	v_lshl_add_u64 v[12:13], s[4:5], 0, v[4:5]
	v_cvt_pk_u8_f32 v7, v7, 3, v11
	global_store_dwordx2 v[12:13], v[8:9], off
	v_lshl_add_u64 v[8:9], s[4:5], 0, v[2:3]
	v_xor_b32_e32 v10, 0x80808080, v10
	v_xor_b32_e32 v11, 0x80808080, v7
	global_store_dwordx2 v[8:9], v[10:11], off
	s_add_i32 s0, s0, 8
	s_ashr_i32 s4, s0, 4
	s_mul_hi_i32 s5, s4, 0x2e8ba2e9
	s_lshr_b32 s7, s5, 31
	s_ashr_i32 s5, s5, 1
	s_add_i32 s7, s5, s7
	s_mul_i32 s5, s7, 11
	s_sub_i32 s4, s4, s5
	s_mul_i32 s5, s66, 11
	s_add_i32 s8, s4, s5
	s_lshl_b32 s11, s8, 1
	s_add_i32 s10, s7, s13
	s_or_b32 s11, s11, s3
	s_and_b32 s6, s0, 15
	s_bfe_u32 s9, s0, 0x30001
	s_waitcnt vmcnt(20)
; #define GAS __attribute__((address_space(1)))
; __device__ __forceinline__ float bf_lo(unsigned w) { return __uint_as_float(w << 16); }
; __device__ __forceinline__ float bf_hi(unsigned w) { return __uint_as_float(w & 0xffff0000u); }
; __device__ __forceinline__ void phase_hidconv(LAS unsigned char* lds, const bf16_t* HIDb, unsigned char* HID8, const float* hmx, float* hrs, int grp, int rank, int wv) {
;     ...
;     for (int ui = wave; ui < 2 * 11 * 16; ui += 8) {
;         const int st8 = ui & 15, kk = (ui >> 4) % 11, h = (ui >> 4) / 11;
;         const int kt8 = mem * 11 + kk, rb = st8 >> 1, h2 = st8 & 1;
;         const GAS char* src = (const GAS char*)HIDb + ((size_t)(2 * pm + h) * KT_F + (2 * kt8 + h2)) * pg8::HTB + (size_t)(rb * 2048) + lane * 16;
;         GAS char* dst = (GAS char*)HID8 + ((size_t)(2 * pm + h) * KT_F8 + kt8) * pg8::HTB + (size_t)(st8 * 1024);
;         const u32x4 a = *(const GAS u32x4*)src, b = *(const GAS u32x4*)(src + 1024);
;         const float s_ = sc[h * 128 + rb * 16 + rr];
;         u32x2 wa, wb;
;         wa.x = cvt_i8x4(bf_lo(a.x) * s_, bf_hi(a.x) * s_, bf_lo(a.y) * s_, bf_hi(a.y) * s_); wa.y = cvt_i8x4(bf_lo(a.z) * s_, bf_hi(a.z) * s_, bf_lo(a.w) * s_, bf_hi(a.w) * s_);
;         wb.x = cvt_i8x4(bf_lo(b.x) * s_, bf_hi(b.x) * s_, bf_lo(b.y) * s_, bf_hi(b.y) * s_); wb.y = cvt_i8x4(bf_lo(b.z) * s_, bf_hi(b.z) * s_, bf_lo(b.w) * s_, bf_hi(b.w) * s_);
;         *(GAS u32x2*)(dst + d0) = wa; *(GAS u32x2*)(dst + d1) = wb;
	v_mov_b32_e32 v8, v88
	v_mov_b32_e32 v9, v89
	v_mov_b32_e32 v10, v90
	v_mov_b32_e32 v11, v91
	v_mov_b32_e32 v12, v92
	v_mov_b32_e32 v13, v93
	v_mov_b32_e32 v14, v94
	v_mov_b32_e32 v15, v95
	s_mul_hi_i32 s5, s10, 44
	s_mul_i32 s10, s10, 44
	s_ashr_i32 s11, s8, 31
	s_add_u32 s4, s10, s8
	s_addc_u32 s5, s5, s11
	s_lshl_b64 s[4:5], s[4:5], 14
	s_add_u32 s4, s1, s4
	s_addc_u32 s5, s2, s5
	s_lshl_b32 s6, s6, 10
	s_add_u32 s4, s4, s6
	s_addc_u32 s5, s5, 0
	s_lshl_b32 s6, s7, 9
	s_add_i32 s6, s40, s6
	s_lshl_b32 s7, s9, 6
	s_add_i32 s6, s6, s7
	v_lshl_add_u32 v7, v6, 2, s6
	ds_read_b32 v7, v7
	v_lshlrev_b32_e32 v16, 16, v8
	v_and_b32_e32 v8, 0xffff0000, v8
	s_waitcnt lgkmcnt(0)
	v_fmaak_f32 v16, v7, v16, 0x43000000
	v_lshlrev_b32_e32 v17, 16, v9
	v_cvt_pk_u8_f32 v16, v16, 0, 0
	v_fmaak_f32 v8, v7, v8, 0x43000000
	v_and_b32_e32 v9, 0xffff0000, v9
	v_cvt_pk_u8_f32 v8, v8, 1, v16
	v_fmaak_f32 v16, v7, v17, 0x43000000
	v_cvt_pk_u8_f32 v8, v16, 2, v8
	v_fmaak_f32 v9, v7, v9, 0x43000000
	v_cvt_pk_u8_f32 v8, v9, 3, v8
	v_lshlrev_b32_e32 v9, 16, v10
	v_and_b32_e32 v10, 0xffff0000, v10
	v_fmaak_f32 v9, v7, v9, 0x43000000
	v_lshlrev_b32_e32 v16, 16, v11
	v_cvt_pk_u8_f32 v9, v9, 0, 0
	v_fmaak_f32 v10, v7, v10, 0x43000000
	v_and_b32_e32 v11, 0xffff0000, v11
	v_cvt_pk_u8_f32 v9, v10, 1, v9
	v_fmaak_f32 v10, v7, v16, 0x43000000
	v_cvt_pk_u8_f32 v9, v10, 2, v9
	v_fmaak_f32 v10, v7, v11, 0x43000000
	v_cvt_pk_u8_f32 v9, v10, 3, v9
	v_lshlrev_b32_e32 v10, 16, v12
	v_and_b32_e32 v11, 0xffff0000, v12
	v_fmaak_f32 v10, v7, v10, 0x43000000
	v_lshlrev_b32_e32 v12, 16, v13
	v_cvt_pk_u8_f32 v10, v10, 0, 0
	v_fmaak_f32 v11, v7, v11, 0x43000000
	v_and_b32_e32 v13, 0xffff0000, v13
	v_cvt_pk_u8_f32 v10, v11, 1, v10
	v_fmaak_f32 v11, v7, v12, 0x43000000
	v_cvt_pk_u8_f32 v10, v11, 2, v10
	v_fmaak_f32 v11, v7, v13, 0x43000000
	v_cvt_pk_u8_f32 v10, v11, 3, v10
	v_lshlrev_b32_e32 v11, 16, v14
	v_and_b32_e32 v12, 0xffff0000, v14
	v_fmaak_f32 v11, v7, v11, 0x43000000
	v_lshlrev_b32_e32 v13, 16, v15
	v_cvt_pk_u8_f32 v11, v11, 0, 0
	v_fmaak_f32 v12, v7, v12, 0x43000000
	v_and_b32_e32 v14, 0xffff0000, v15
	v_cvt_pk_u8_f32 v11, v12, 1, v11
	v_fmaak_f32 v12, v7, v13, 0x43000000
	v_xor_b32_e32 v8, 0x80808080, v8
	v_xor_b32_e32 v9, 0x80808080, v9
	v_cvt_pk_u8_f32 v11, v12, 2, v11
	v_fmaak_f32 v7, v7, v14, 0x43000000
	v_lshl_add_u64 v[12:13], s[4:5], 0, v[4:5]
	v_cvt_pk_u8_f32 v7, v7, 3, v11
	global_store_dwordx2 v[12:13], v[8:9], off
	v_lshl_add_u64 v[8:9], s[4:5], 0, v[2:3]
	v_xor_b32_e32 v10, 0x80808080, v10
	v_xor_b32_e32 v11, 0x80808080, v7
	global_store_dwordx2 v[8:9], v[10:11], off
	s_add_i32 s0, s0, 8
	s_ashr_i32 s4, s0, 4
	s_mul_hi_i32 s5, s4, 0x2e8ba2e9
	s_lshr_b32 s7, s5, 31
	s_ashr_i32 s5, s5, 1
	s_add_i32 s7, s5, s7
	s_mul_i32 s5, s7, 11
	s_sub_i32 s4, s4, s5
	s_mul_i32 s5, s66, 11
	s_add_i32 s8, s4, s5
	s_lshl_b32 s11, s8, 1
	s_add_i32 s10, s7, s13
	s_or_b32 s11, s11, s3
	s_and_b32 s6, s0, 15
	s_bfe_u32 s9, s0, 0x30001
	s_waitcnt vmcnt(20)
	v_mov_b32_e32 v8, v96
	v_mov_b32_e32 v9, v97
	v_mov_b32_e32 v10, v98
	v_mov_b32_e32 v11, v99
	v_mov_b32_e32 v12, v100
	v_mov_b32_e32 v13, v101
	v_mov_b32_e32 v14, v102
	v_mov_b32_e32 v15, v103
	s_mul_hi_i32 s5, s10, 44
	s_mul_i32 s10, s10, 44
	s_ashr_i32 s11, s8, 31
	s_add_u32 s4, s10, s8
	s_addc_u32 s5, s5, s11
	s_lshl_b64 s[4:5], s[4:5], 14
	s_add_u32 s4, s1, s4
	s_addc_u32 s5, s2, s5
	s_lshl_b32 s6, s6, 10
	s_add_u32 s4, s4, s6
	s_addc_u32 s5, s5, 0
	s_lshl_b32 s6, s7, 9
	s_add_i32 s6, s40, s6
	s_lshl_b32 s7, s9, 6
	s_add_i32 s6, s6, s7
	v_lshl_add_u32 v7, v6, 2, s6
	ds_read_b32 v7, v7
	v_lshlrev_b32_e32 v16, 16, v8
	v_and_b32_e32 v8, 0xffff0000, v8
	s_waitcnt lgkmcnt(0)
	v_fmaak_f32 v16, v7, v16, 0x43000000
	v_lshlrev_b32_e32 v17, 16, v9
	v_cvt_pk_u8_f32 v16, v16, 0, 0
	v_fmaak_f32 v8, v7, v8, 0x43000000
	v_and_b32_e32 v9, 0xffff0000, v9
	v_cvt_pk_u8_f32 v8, v8, 1, v16
	v_fmaak_f32 v16, v7, v17, 0x43000000
	v_cvt_pk_u8_f32 v8, v16, 2, v8
	v_fmaak_f32 v9, v7, v9, 0x43000000
	v_cvt_pk_u8_f32 v8, v9, 3, v8
	v_lshlrev_b32_e32 v9, 16, v10
	v_and_b32_e32 v10, 0xffff0000, v10
	v_fmaak_f32 v9, v7, v9, 0x43000000
	v_lshlrev_b32_e32 v16, 16, v11
	v_cvt_pk_u8_f32 v9, v9, 0, 0
	v_fmaak_f32 v10, v7, v10, 0x43000000
	v_and_b32_e32 v11, 0xffff0000, v11
	v_cvt_pk_u8_f32 v9, v10, 1, v9
	v_fmaak_f32 v10, v7, v16, 0x43000000
	v_cvt_pk_u8_f32 v9, v10, 2, v9
	v_fmaak_f32 v10, v7, v11, 0x43000000
	v_cvt_pk_u8_f32 v9, v10, 3, v9
	v_lshlrev_b32_e32 v10, 16, v12
	v_and_b32_e32 v11, 0xffff0000, v12
	v_fmaak_f32 v10, v7, v10, 0x43000000
	v_lshlrev_b32_e32 v12, 16, v13
	v_cvt_pk_u8_f32 v10, v10, 0, 0
	v_fmaak_f32 v11, v7, v11, 0x43000000
	v_and_b32_e32 v13, 0xffff0000, v13
	v_cvt_pk_u8_f32 v10, v11, 1, v10
	v_fmaak_f32 v11, v7, v12, 0x43000000
	v_cvt_pk_u8_f32 v10, v11, 2, v10
	v_fmaak_f32 v11, v7, v13, 0x43000000
	v_cvt_pk_u8_f32 v10, v11, 3, v10
	v_lshlrev_b32_e32 v11, 16, v14
	v_and_b32_e32 v12, 0xffff0000, v14
	v_fmaak_f32 v11, v7, v11, 0x43000000
	v_lshlrev_b32_e32 v13, 16, v15
	v_cvt_pk_u8_f32 v11, v11, 0, 0
	v_fmaak_f32 v12, v7, v12, 0x43000000
	v_and_b32_e32 v14, 0xffff0000, v15
	v_cvt_pk_u8_f32 v11, v12, 1, v11
	v_fmaak_f32 v12, v7, v13, 0x43000000
	v_xor_b32_e32 v8, 0x80808080, v8
	v_xor_b32_e32 v9, 0x80808080, v9
	v_cvt_pk_u8_f32 v11, v12, 2, v11
	v_fmaak_f32 v7, v7, v14, 0x43000000
	v_lshl_add_u64 v[12:13], s[4:5], 0, v[4:5]
	v_cvt_pk_u8_f32 v7, v7, 3, v11
	global_store_dwordx2 v[12:13], v[8:9], off
	v_lshl_add_u64 v[8:9], s[4:5], 0, v[2:3]
	v_xor_b32_e32 v10, 0x80808080, v10
	v_xor_b32_e32 v11, 0x80808080, v7
	global_store_dwordx2 v[8:9], v[10:11], off
	s_add_i32 s0, s0, 8
	s_ashr_i32 s4, s0, 4
	s_mul_hi_i32 s5, s4, 0x2e8ba2e9
	s_lshr_b32 s7, s5, 31
	s_ashr_i32 s5, s5, 1
	s_add_i32 s7, s5, s7
	s_mul_i32 s5, s7, 11
	s_sub_i32 s4, s4, s5
	s_mul_i32 s5, s66, 11
	s_add_i32 s8, s4, s5
	s_lshl_b32 s11, s8, 1
	s_add_i32 s10, s7, s13
	s_or_b32 s11, s11, s3
	s_and_b32 s6, s0, 15
	s_bfe_u32 s9, s0, 0x30001
	s_waitcnt vmcnt(20)
; #define GAS __attribute__((address_space(1)))
; __device__ __forceinline__ float bf_lo(unsigned w) { return __uint_as_float(w << 16); }
; __device__ __forceinline__ float bf_hi(unsigned w) { return __uint_as_float(w & 0xffff0000u); }
; __device__ __forceinline__ void phase_hidconv(LAS unsigned char* lds, const bf16_t* HIDb, unsigned char* HID8, const float* hmx, float* hrs, int grp, int rank, int wv) {
;     ...
;     for (int ui = wave; ui < 2 * 11 * 16; ui += 8) {
;         const int st8 = ui & 15, kk = (ui >> 4) % 11, h = (ui >> 4) / 11;
;         const int kt8 = mem * 11 + kk, rb = st8 >> 1, h2 = st8 & 1;
;         const GAS char* src = (const GAS char*)HIDb + ((size_t)(2 * pm + h) * KT_F + (2 * kt8 + h2)) * pg8::HTB + (size_t)(rb * 2048) + lane * 16;
;         GAS char* dst = (GAS char*)HID8 + ((size_t)(2 * pm + h) * KT_F8 + kt8) * pg8::HTB + (size_t)(st8 * 1024);
;         const u32x4 a = *(const GAS u32x4*)src, b = *(const GAS u32x4*)(src + 1024);
;         const float s_ = sc[h * 128 + rb * 16 + rr];
;         u32x2 wa, wb;
;         wa.x = cvt_i8x4(bf_lo(a.x) * s_, bf_hi(a.x) * s_, bf_lo(a.y) * s_, bf_hi(a.y) * s_); wa.y = cvt_i8x4(bf_lo(a.z) * s_, bf_hi(a.z) * s_, bf_lo(a.w) * s_, bf_hi(a.w) * s_);
;         wb.x = cvt_i8x4(bf_lo(b.x) * s_, bf_hi(b.x) * s_, bf_lo(b.y) * s_, bf_hi(b.y) * s_); wb.y = cvt_i8x4(bf_lo(b.z) * s_, bf_hi(b.z) * s_, bf_lo(b.w) * s_, bf_hi(b.w) * s_);
;         *(GAS u32x2*)(dst + d0) = wa; *(GAS u32x2*)(dst + d1) = wb;
	v_mov_b32_e32 v8, v104
	v_mov_b32_e32 v9, v105
	v_mov_b32_e32 v10, v106
	v_mov_b32_e32 v11, v107
	v_mov_b32_e32 v12, v108
	v_mov_b32_e32 v13, v109
	v_mov_b32_e32 v14, v110
	v_mov_b32_e32 v15, v111
	s_mul_hi_i32 s5, s10, 44
	s_mul_i32 s10, s10, 44
	s_ashr_i32 s11, s8, 31
	s_add_u32 s4, s10, s8
	s_addc_u32 s5, s5, s11
	s_lshl_b64 s[4:5], s[4:5], 14
	s_add_u32 s4, s1, s4
	s_addc_u32 s5, s2, s5
	s_lshl_b32 s6, s6, 10
	s_add_u32 s4, s4, s6
	s_addc_u32 s5, s5, 0
	s_lshl_b32 s6, s7, 9
	s_add_i32 s6, s40, s6
	s_lshl_b32 s7, s9, 6
	s_add_i32 s6, s6, s7
	v_lshl_add_u32 v7, v6, 2, s6
	ds_read_b32 v7, v7
	v_lshlrev_b32_e32 v16, 16, v8
	v_and_b32_e32 v8, 0xffff0000, v8
	s_waitcnt lgkmcnt(0)
	v_fmaak_f32 v16, v7, v16, 0x43000000
	v_lshlrev_b32_e32 v17, 16, v9
	v_cvt_pk_u8_f32 v16, v16, 0, 0
	v_fmaak_f32 v8, v7, v8, 0x43000000
	v_and_b32_e32 v9, 0xffff0000, v9
	v_cvt_pk_u8_f32 v8, v8, 1, v16
	v_fmaak_f32 v16, v7, v17, 0x43000000
	v_cvt_pk_u8_f32 v8, v16, 2, v8
	v_fmaak_f32 v9, v7, v9, 0x43000000
	v_cvt_pk_u8_f32 v8, v9, 3, v8
	v_lshlrev_b32_e32 v9, 16, v10
	v_and_b32_e32 v10, 0xffff0000, v10
	v_fmaak_f32 v9, v7, v9, 0x43000000
	v_lshlrev_b32_e32 v16, 16, v11
	v_cvt_pk_u8_f32 v9, v9, 0, 0
	v_fmaak_f32 v10, v7, v10, 0x43000000
	v_and_b32_e32 v11, 0xffff0000, v11
	v_cvt_pk_u8_f32 v9, v10, 1, v9
	v_fmaak_f32 v10, v7, v16, 0x43000000
	v_cvt_pk_u8_f32 v9, v10, 2, v9
	v_fmaak_f32 v10, v7, v11, 0x43000000
	v_cvt_pk_u8_f32 v9, v10, 3, v9
	v_lshlrev_b32_e32 v10, 16, v12
	v_and_b32_e32 v11, 0xffff0000, v12
	v_fmaak_f32 v10, v7, v10, 0x43000000
	v_lshlrev_b32_e32 v12, 16, v13
	v_cvt_pk_u8_f32 v10, v10, 0, 0
	v_fmaak_f32 v11, v7, v11, 0x43000000
	v_and_b32_e32 v13, 0xffff0000, v13
	v_cvt_pk_u8_f32 v10, v11, 1, v10
	v_fmaak_f32 v11, v7, v12, 0x43000000
	v_cvt_pk_u8_f32 v10, v11, 2, v10
	v_fmaak_f32 v11, v7, v13, 0x43000000
	v_cvt_pk_u8_f32 v10, v11, 3, v10
	v_lshlrev_b32_e32 v11, 16, v14
	v_and_b32_e32 v12, 0xffff0000, v14
	v_fmaak_f32 v11, v7, v11, 0x43000000
	v_lshlrev_b32_e32 v13, 16, v15
	v_cvt_pk_u8_f32 v11, v11, 0, 0
	v_fmaak_f32 v12, v7, v12, 0x43000000
	v_and_b32_e32 v14, 0xffff0000, v15
	v_cvt_pk_u8_f32 v11, v12, 1, v11
	v_fmaak_f32 v12, v7, v13, 0x43000000
	v_xor_b32_e32 v8, 0x80808080, v8
	v_xor_b32_e32 v9, 0x80808080, v9
	v_cvt_pk_u8_f32 v11, v12, 2, v11
	v_fmaak_f32 v7, v7, v14, 0x43000000
	v_lshl_add_u64 v[12:13], s[4:5], 0, v[4:5]
	v_cvt_pk_u8_f32 v7, v7, 3, v11
	global_store_dwordx2 v[12:13], v[8:9], off
	v_lshl_add_u64 v[8:9], s[4:5], 0, v[2:3]
	v_xor_b32_e32 v10, 0x80808080, v10
	v_xor_b32_e32 v11, 0x80808080, v7
	global_store_dwordx2 v[8:9], v[10:11], off
	s_add_i32 s0, s0, 8
	s_ashr_i32 s4, s0, 4
	s_mul_hi_i32 s5, s4, 0x2e8ba2e9
	s_lshr_b32 s7, s5, 31
	s_ashr_i32 s5, s5, 1
	s_add_i32 s7, s5, s7
	s_mul_i32 s5, s7, 11
	s_sub_i32 s4, s4, s5
	s_mul_i32 s5, s66, 11
	s_add_i32 s8, s4, s5
	s_lshl_b32 s11, s8, 1
	s_add_i32 s10, s7, s13
	s_or_b32 s11, s11, s3
	s_and_b32 s6, s0, 15
	s_bfe_u32 s9, s0, 0x30001
	s_waitcnt vmcnt(20)
	v_mov_b32_e32 v8, v112
	v_mov_b32_e32 v9, v113
	v_mov_b32_e32 v10, v114
	v_mov_b32_e32 v11, v115
	v_mov_b32_e32 v12, v116
	v_mov_b32_e32 v13, v117
	v_mov_b32_e32 v14, v118
	v_mov_b32_e32 v15, v119
	s_mul_hi_i32 s5, s10, 44
	s_mul_i32 s10, s10, 44
	s_ashr_i32 s11, s8, 31
	s_add_u32 s4, s10, s8
	s_addc_u32 s5, s5, s11
	s_lshl_b64 s[4:5], s[4:5], 14
	s_add_u32 s4, s1, s4
	s_addc_u32 s5, s2, s5
	s_lshl_b32 s6, s6, 10
	s_add_u32 s4, s4, s6
	s_addc_u32 s5, s5, 0
	s_lshl_b32 s6, s7, 9
	s_add_i32 s6, s40, s6
	s_lshl_b32 s7, s9, 6
	s_add_i32 s6, s6, s7
	v_lshl_add_u32 v7, v6, 2, s6
	ds_read_b32 v7, v7
	v_lshlrev_b32_e32 v16, 16, v8
	v_and_b32_e32 v8, 0xffff0000, v8
	s_waitcnt lgkmcnt(0)
	v_fmaak_f32 v16, v7, v16, 0x43000000
	v_lshlrev_b32_e32 v17, 16, v9
	v_cvt_pk_u8_f32 v16, v16, 0, 0
	v_fmaak_f32 v8, v7, v8, 0x43000000
	v_and_b32_e32 v9, 0xffff0000, v9
	v_cvt_pk_u8_f32 v8, v8, 1, v16
	v_fmaak_f32 v16, v7, v17, 0x43000000
	v_cvt_pk_u8_f32 v8, v16, 2, v8
	v_fmaak_f32 v9, v7, v9, 0x43000000
	v_cvt_pk_u8_f32 v8, v9, 3, v8
	v_lshlrev_b32_e32 v9, 16, v10
	v_and_b32_e32 v10, 0xffff0000, v10
	v_fmaak_f32 v9, v7, v9, 0x43000000
	v_lshlrev_b32_e32 v16, 16, v11
	v_cvt_pk_u8_f32 v9, v9, 0, 0
	v_fmaak_f32 v10, v7, v10, 0x43000000
	v_and_b32_e32 v11, 0xffff0000, v11
	v_cvt_pk_u8_f32 v9, v10, 1, v9
	v_fmaak_f32 v10, v7, v16, 0x43000000
	v_cvt_pk_u8_f32 v9, v10, 2, v9
	v_fmaak_f32 v10, v7, v11, 0x43000000
	v_cvt_pk_u8_f32 v9, v10, 3, v9
	v_lshlrev_b32_e32 v10, 16, v12
	v_and_b32_e32 v11, 0xffff0000, v12
	v_fmaak_f32 v10, v7, v10, 0x43000000
	v_lshlrev_b32_e32 v12, 16, v13
	v_cvt_pk_u8_f32 v10, v10, 0, 0
	v_fmaak_f32 v11, v7, v11, 0x43000000
	v_and_b32_e32 v13, 0xffff0000, v13
	v_cvt_pk_u8_f32 v10, v11, 1, v10
	v_fmaak_f32 v11, v7, v12, 0x43000000
	v_cvt_pk_u8_f32 v10, v11, 2, v10
	v_fmaak_f32 v11, v7, v13, 0x43000000
	v_cvt_pk_u8_f32 v10, v11, 3, v10
	v_lshlrev_b32_e32 v11, 16, v14
	v_and_b32_e32 v12, 0xffff0000, v14
	v_fmaak_f32 v11, v7, v11, 0x43000000
	v_lshlrev_b32_e32 v13, 16, v15
	v_cvt_pk_u8_f32 v11, v11, 0, 0
	v_fmaak_f32 v12, v7, v12, 0x43000000
	v_and_b32_e32 v14, 0xffff0000, v15
	v_cvt_pk_u8_f32 v11, v12, 1, v11
	v_fmaak_f32 v12, v7, v13, 0x43000000
	v_xor_b32_e32 v8, 0x80808080, v8
	v_xor_b32_e32 v9, 0x80808080, v9
	v_cvt_pk_u8_f32 v11, v12, 2, v11
	v_fmaak_f32 v7, v7, v14, 0x43000000
	v_lshl_add_u64 v[12:13], s[4:5], 0, v[4:5]
	v_cvt_pk_u8_f32 v7, v7, 3, v11
	global_store_dwordx2 v[12:13], v[8:9], off
	v_lshl_add_u64 v[8:9], s[4:5], 0, v[2:3]
	v_xor_b32_e32 v10, 0x80808080, v10
	v_xor_b32_e32 v11, 0x80808080, v7
	global_store_dwordx2 v[8:9], v[10:11], off
	s_add_i32 s0, s0, 8
	s_ashr_i32 s4, s0, 4
	s_mul_hi_i32 s5, s4, 0x2e8ba2e9
	s_lshr_b32 s7, s5, 31
	s_ashr_i32 s5, s5, 1
	s_add_i32 s7, s5, s7
	s_mul_i32 s5, s7, 11
	s_sub_i32 s4, s4, s5
	s_mul_i32 s5, s66, 11
	s_add_i32 s8, s4, s5
	s_lshl_b32 s11, s8, 1
	s_add_i32 s10, s7, s13
	s_or_b32 s11, s11, s3
	s_and_b32 s6, s0, 15
	s_bfe_u32 s9, s0, 0x30001
	s_waitcnt vmcnt(20)
; #define GAS __attribute__((address_space(1)))
; __device__ __forceinline__ float bf_lo(unsigned w) { return __uint_as_float(w << 16); }
; __device__ __forceinline__ float bf_hi(unsigned w) { return __uint_as_float(w & 0xffff0000u); }
; __device__ __forceinline__ void phase_hidconv(LAS unsigned char* lds, const bf16_t* HIDb, unsigned char* HID8, const float* hmx, float* hrs, int grp, int rank, int wv) {
;     ...
;     for (int ui = wave; ui < 2 * 11 * 16; ui += 8) {
;         const int st8 = ui & 15, kk = (ui >> 4) % 11, h = (ui >> 4) / 11;
;         const int kt8 = mem * 11 + kk, rb = st8 >> 1, h2 = st8 & 1;
;         const GAS char* src = (const GAS char*)HIDb + ((size_t)(2 * pm + h) * KT_F + (2 * kt8 + h2)) * pg8::HTB + (size_t)(rb * 2048) + lane * 16;
;         GAS char* dst = (GAS char*)HID8 + ((size_t)(2 * pm + h) * KT_F8 + kt8) * pg8::HTB + (size_t)(st8 * 1024);
;         const u32x4 a = *(const GAS u32x4*)src, b = *(const GAS u32x4*)(src + 1024);
;         const float s_ = sc[h * 128 + rb * 16 + rr];
;         u32x2 wa, wb;
;         wa.x = cvt_i8x4(bf_lo(a.x) * s_, bf_hi(a.x) * s_, bf_lo(a.y) * s_, bf_hi(a.y) * s_); wa.y = cvt_i8x4(bf_lo(a.z) * s_, bf_hi(a.z) * s_, bf_lo(a.w) * s_, bf_hi(a.w) * s_);
;         wb.x = cvt_i8x4(bf_lo(b.x) * s_, bf_hi(b.x) * s_, bf_lo(b.y) * s_, bf_hi(b.y) * s_); wb.y = cvt_i8x4(bf_lo(b.z) * s_, bf_hi(b.z) * s_, bf_lo(b.w) * s_, bf_hi(b.w) * s_);
;         *(GAS u32x2*)(dst + d0) = wa; *(GAS u32x2*)(dst + d1) = wb;
	v_mov_b32_e32 v8, v120
	v_mov_b32_e32 v9, v121
	v_mov_b32_e32 v10, v122
	v_mov_b32_e32 v11, v123
	v_mov_b32_e32 v12, v124
	v_mov_b32_e32 v13, v125
	v_mov_b32_e32 v14, v126
	v_mov_b32_e32 v15, v127
	s_mul_hi_i32 s5, s10, 44
	s_mul_i32 s10, s10, 44
	s_ashr_i32 s11, s8, 31
	s_add_u32 s4, s10, s8
	s_addc_u32 s5, s5, s11
	s_lshl_b64 s[4:5], s[4:5], 14
	s_add_u32 s4, s1, s4
	s_addc_u32 s5, s2, s5
	s_lshl_b32 s6, s6, 10
	s_add_u32 s4, s4, s6
	s_addc_u32 s5, s5, 0
	s_lshl_b32 s6, s7, 9
	s_add_i32 s6, s40, s6
	s_lshl_b32 s7, s9, 6
	s_add_i32 s6, s6, s7
	v_lshl_add_u32 v7, v6, 2, s6
	ds_read_b32 v7, v7
	v_lshlrev_b32_e32 v16, 16, v8
	v_and_b32_e32 v8, 0xffff0000, v8
	s_waitcnt lgkmcnt(0)
	v_fmaak_f32 v16, v7, v16, 0x43000000
	v_lshlrev_b32_e32 v17, 16, v9
	v_cvt_pk_u8_f32 v16, v16, 0, 0
	v_fmaak_f32 v8, v7, v8, 0x43000000
	v_and_b32_e32 v9, 0xffff0000, v9
	v_cvt_pk_u8_f32 v8, v8, 1, v16
	v_fmaak_f32 v16, v7, v17, 0x43000000
	v_cvt_pk_u8_f32 v8, v16, 2, v8
	v_fmaak_f32 v9, v7, v9, 0x43000000
	v_cvt_pk_u8_f32 v8, v9, 3, v8
	v_lshlrev_b32_e32 v9, 16, v10
	v_and_b32_e32 v10, 0xffff0000, v10
	v_fmaak_f32 v9, v7, v9, 0x43000000
	v_lshlrev_b32_e32 v16, 16, v11
	v_cvt_pk_u8_f32 v9, v9, 0, 0
	v_fmaak_f32 v10, v7, v10, 0x43000000
	v_and_b32_e32 v11, 0xffff0000, v11
	v_cvt_pk_u8_f32 v9, v10, 1, v9
	v_fmaak_f32 v10, v7, v16, 0x43000000
	v_cvt_pk_u8_f32 v9, v10, 2, v9
	v_fmaak_f32 v10, v7, v11, 0x43000000
	v_cvt_pk_u8_f32 v9, v10, 3, v9
	v_lshlrev_b32_e32 v10, 16, v12
	v_and_b32_e32 v11, 0xffff0000, v12
	v_fmaak_f32 v10, v7, v10, 0x43000000
	v_lshlrev_b32_e32 v12, 16, v13
	v_cvt_pk_u8_f32 v10, v10, 0, 0
	v_fmaak_f32 v11, v7, v11, 0x43000000
	v_and_b32_e32 v13, 0xffff0000, v13
	v_cvt_pk_u8_f32 v10, v11, 1, v10
	v_fmaak_f32 v11, v7, v12, 0x43000000
	v_cvt_pk_u8_f32 v10, v11, 2, v10
	v_fmaak_f32 v11, v7, v13, 0x43000000
	v_cvt_pk_u8_f32 v10, v11, 3, v10
	v_lshlrev_b32_e32 v11, 16, v14
	v_and_b32_e32 v12, 0xffff0000, v14
	v_fmaak_f32 v11, v7, v11, 0x43000000
	v_lshlrev_b32_e32 v13, 16, v15
	v_cvt_pk_u8_f32 v11, v11, 0, 0
	v_fmaak_f32 v12, v7, v12, 0x43000000
	v_and_b32_e32 v14, 0xffff0000, v15
	v_cvt_pk_u8_f32 v11, v12, 1, v11
	v_fmaak_f32 v12, v7, v13, 0x43000000
	v_xor_b32_e32 v8, 0x80808080, v8
	v_xor_b32_e32 v9, 0x80808080, v9
	v_cvt_pk_u8_f32 v11, v12, 2, v11
	v_fmaak_f32 v7, v7, v14, 0x43000000
	v_lshl_add_u64 v[12:13], s[4:5], 0, v[4:5]
	v_cvt_pk_u8_f32 v7, v7, 3, v11
	global_store_dwordx2 v[12:13], v[8:9], off
	v_lshl_add_u64 v[8:9], s[4:5], 0, v[2:3]
	v_xor_b32_e32 v10, 0x80808080, v10
	v_xor_b32_e32 v11, 0x80808080, v7
	global_store_dwordx2 v[8:9], v[10:11], off
	s_add_i32 s0, s0, 8
	s_ashr_i32 s4, s0, 4
	s_mul_hi_i32 s5, s4, 0x2e8ba2e9
	s_lshr_b32 s7, s5, 31
	s_ashr_i32 s5, s5, 1
	s_add_i32 s7, s5, s7
	s_mul_i32 s5, s7, 11
	s_sub_i32 s4, s4, s5
	s_mul_i32 s5, s66, 11
	s_add_i32 s8, s4, s5
	s_lshl_b32 s11, s8, 1
	s_add_i32 s10, s7, s13
	s_or_b32 s11, s11, s3
	s_and_b32 s6, s0, 15
	s_bfe_u32 s9, s0, 0x30001
	s_waitcnt vmcnt(20)
	v_mov_b32_e32 v8, v128
	v_mov_b32_e32 v9, v129
	v_mov_b32_e32 v10, v130
	v_mov_b32_e32 v11, v131
	v_mov_b32_e32 v12, v132
	v_mov_b32_e32 v13, v133
	v_mov_b32_e32 v14, v134
	v_mov_b32_e32 v15, v135
	s_mul_hi_i32 s5, s10, 44
	s_mul_i32 s10, s10, 44
	s_ashr_i32 s11, s8, 31
	s_add_u32 s4, s10, s8
	s_addc_u32 s5, s5, s11
	s_lshl_b64 s[4:5], s[4:5], 14
	s_add_u32 s4, s1, s4
	s_addc_u32 s5, s2, s5
	s_lshl_b32 s6, s6, 10
	s_add_u32 s4, s4, s6
	s_addc_u32 s5, s5, 0
	s_lshl_b32 s6, s7, 9
	s_add_i32 s6, s40, s6
	s_lshl_b32 s7, s9, 6
	s_add_i32 s6, s6, s7
	v_lshl_add_u32 v7, v6, 2, s6
	ds_read_b32 v7, v7
	v_lshlrev_b32_e32 v16, 16, v8
	v_and_b32_e32 v8, 0xffff0000, v8
	s_waitcnt lgkmcnt(0)
	v_fmaak_f32 v16, v7, v16, 0x43000000
	v_lshlrev_b32_e32 v17, 16, v9
	v_cvt_pk_u8_f32 v16, v16, 0, 0
	v_fmaak_f32 v8, v7, v8, 0x43000000
	v_and_b32_e32 v9, 0xffff0000, v9
	v_cvt_pk_u8_f32 v8, v8, 1, v16
	v_fmaak_f32 v16, v7, v17, 0x43000000
	v_cvt_pk_u8_f32 v8, v16, 2, v8
	v_fmaak_f32 v9, v7, v9, 0x43000000
	v_cvt_pk_u8_f32 v8, v9, 3, v8
	v_lshlrev_b32_e32 v9, 16, v10
	v_and_b32_e32 v10, 0xffff0000, v10
	v_fmaak_f32 v9, v7, v9, 0x43000000
	v_lshlrev_b32_e32 v16, 16, v11
	v_cvt_pk_u8_f32 v9, v9, 0, 0
	v_fmaak_f32 v10, v7, v10, 0x43000000
	v_and_b32_e32 v11, 0xffff0000, v11
	v_cvt_pk_u8_f32 v9, v10, 1, v9
	v_fmaak_f32 v10, v7, v16, 0x43000000
	v_cvt_pk_u8_f32 v9, v10, 2, v9
	v_fmaak_f32 v10, v7, v11, 0x43000000
	v_cvt_pk_u8_f32 v9, v10, 3, v9
	v_lshlrev_b32_e32 v10, 16, v12
	v_and_b32_e32 v11, 0xffff0000, v12
	v_fmaak_f32 v10, v7, v10, 0x43000000
	v_lshlrev_b32_e32 v12, 16, v13
	v_cvt_pk_u8_f32 v10, v10, 0, 0
	v_fmaak_f32 v11, v7, v11, 0x43000000
	v_and_b32_e32 v13, 0xffff0000, v13
	v_cvt_pk_u8_f32 v10, v11, 1, v10
	v_fmaak_f32 v11, v7, v12, 0x43000000
	v_cvt_pk_u8_f32 v10, v11, 2, v10
	v_fmaak_f32 v11, v7, v13, 0x43000000
	v_cvt_pk_u8_f32 v10, v11, 3, v10
	v_lshlrev_b32_e32 v11, 16, v14
	v_and_b32_e32 v12, 0xffff0000, v14
	v_fmaak_f32 v11, v7, v11, 0x43000000
	v_lshlrev_b32_e32 v13, 16, v15
	v_cvt_pk_u8_f32 v11, v11, 0, 0
	v_fmaak_f32 v12, v7, v12, 0x43000000
	v_and_b32_e32 v14, 0xffff0000, v15
	v_cvt_pk_u8_f32 v11, v12, 1, v11
	v_fmaak_f32 v12, v7, v13, 0x43000000
	v_xor_b32_e32 v8, 0x80808080, v8
	v_xor_b32_e32 v9, 0x80808080, v9
	v_cvt_pk_u8_f32 v11, v12, 2, v11
	v_fmaak_f32 v7, v7, v14, 0x43000000
	v_lshl_add_u64 v[12:13], s[4:5], 0, v[4:5]
	v_cvt_pk_u8_f32 v7, v7, 3, v11
	global_store_dwordx2 v[12:13], v[8:9], off
	v_lshl_add_u64 v[8:9], s[4:5], 0, v[2:3]
	v_xor_b32_e32 v10, 0x80808080, v10
	v_xor_b32_e32 v11, 0x80808080, v7
	global_store_dwordx2 v[8:9], v[10:11], off
	s_add_i32 s0, s0, 8
	s_ashr_i32 s4, s0, 4
	s_mul_hi_i32 s5, s4, 0x2e8ba2e9
	s_lshr_b32 s7, s5, 31
	s_ashr_i32 s5, s5, 1
	s_add_i32 s7, s5, s7
	s_mul_i32 s5, s7, 11
	s_sub_i32 s4, s4, s5
	s_mul_i32 s5, s66, 11
	s_add_i32 s8, s4, s5
	s_lshl_b32 s11, s8, 1
	s_add_i32 s10, s7, s13
	s_or_b32 s11, s11, s3
	s_and_b32 s6, s0, 15
	s_bfe_u32 s9, s0, 0x30001
	s_waitcnt vmcnt(20)
; #define GAS __attribute__((address_space(1)))
; __device__ __forceinline__ float bf_lo(unsigned w) { return __uint_as_float(w << 16); }
; __device__ __forceinline__ float bf_hi(unsigned w) { return __uint_as_float(w & 0xffff0000u); }
; __device__ __forceinline__ void phase_hidconv(LAS unsigned char* lds, const bf16_t* HIDb, unsigned char* HID8, const float* hmx, float* hrs, int grp, int rank, int wv) {
;     ...
;     for (int ui = wave; ui < 2 * 11 * 16; ui += 8) {
;         const int st8 = ui & 15, kk = (ui >> 4) % 11, h = (ui >> 4) / 11;
;         const int kt8 = mem * 11 + kk, rb = st8 >> 1, h2 = st8 & 1;
;         const GAS char* src = (const GAS char*)HIDb + ((size_t)(2 * pm + h) * KT_F + (2 * kt8 + h2)) * pg8::HTB + (size_t)(rb * 2048) + lane * 16;
;         GAS char* dst = (GAS char*)HID8 + ((size_t)(2 * pm + h) * KT_F8 + kt8) * pg8::HTB + (size_t)(st8 * 1024);
;         const u32x4 a = *(const GAS u32x4*)src, b = *(const GAS u32x4*)(src + 1024);
;         const float s_ = sc[h * 128 + rb * 16 + rr];
;         u32x2 wa, wb;
;         wa.x = cvt_i8x4(bf_lo(a.x) * s_, bf_hi(a.x) * s_, bf_lo(a.y) * s_, bf_hi(a.y) * s_); wa.y = cvt_i8x4(bf_lo(a.z) * s_, bf_hi(a.z) * s_, bf_lo(a.w) * s_, bf_hi(a.w) * s_);
;         wb.x = cvt_i8x4(bf_lo(b.x) * s_, bf_hi(b.x) * s_, bf_lo(b.y) * s_, bf_hi(b.y) * s_); wb.y = cvt_i8x4(bf_lo(b.z) * s_, bf_hi(b.z) * s_, bf_lo(b.w) * s_, bf_hi(b.w) * s_);
;         *(GAS u32x2*)(dst + d0) = wa; *(GAS u32x2*)(dst + d1) = wb;
	v_mov_b32_e32 v8, v136
	v_mov_b32_e32 v9, v137
	v_mov_b32_e32 v10, v138
	v_mov_b32_e32 v11, v139
	v_mov_b32_e32 v12, v140
	v_mov_b32_e32 v13, v141
	v_mov_b32_e32 v14, v142
	v_mov_b32_e32 v15, v143
	s_mul_hi_i32 s5, s10, 44
	s_mul_i32 s10, s10, 44
	s_ashr_i32 s11, s8, 31
	s_add_u32 s4, s10, s8
	s_addc_u32 s5, s5, s11
	s_lshl_b64 s[4:5], s[4:5], 14
	s_add_u32 s4, s1, s4
	s_addc_u32 s5, s2, s5
	s_lshl_b32 s6, s6, 10
	s_add_u32 s4, s4, s6
	s_addc_u32 s5, s5, 0
	s_lshl_b32 s6, s7, 9
	s_add_i32 s6, s40, s6
	s_lshl_b32 s7, s9, 6
	s_add_i32 s6, s6, s7
	v_lshl_add_u32 v7, v6, 2, s6
	ds_read_b32 v7, v7
	v_lshlrev_b32_e32 v16, 16, v8
	v_and_b32_e32 v8, 0xffff0000, v8
	s_waitcnt lgkmcnt(0)
	v_fmaak_f32 v16, v7, v16, 0x43000000
	v_lshlrev_b32_e32 v17, 16, v9
	v_cvt_pk_u8_f32 v16, v16, 0, 0
	v_fmaak_f32 v8, v7, v8, 0x43000000
	v_and_b32_e32 v9, 0xffff0000, v9
	v_cvt_pk_u8_f32 v8, v8, 1, v16
	v_fmaak_f32 v16, v7, v17, 0x43000000
	v_cvt_pk_u8_f32 v8, v16, 2, v8
	v_fmaak_f32 v9, v7, v9, 0x43000000
	v_cvt_pk_u8_f32 v8, v9, 3, v8
	v_lshlrev_b32_e32 v9, 16, v10
	v_and_b32_e32 v10, 0xffff0000, v10
	v_fmaak_f32 v9, v7, v9, 0x43000000
	v_lshlrev_b32_e32 v16, 16, v11
	v_cvt_pk_u8_f32 v9, v9, 0, 0
	v_fmaak_f32 v10, v7, v10, 0x43000000
	v_and_b32_e32 v11, 0xffff0000, v11
	v_cvt_pk_u8_f32 v9, v10, 1, v9
	v_fmaak_f32 v10, v7, v16, 0x43000000
	v_cvt_pk_u8_f32 v9, v10, 2, v9
	v_fmaak_f32 v10, v7, v11, 0x43000000
	v_cvt_pk_u8_f32 v9, v10, 3, v9
	v_lshlrev_b32_e32 v10, 16, v12
	v_and_b32_e32 v11, 0xffff0000, v12
	v_fmaak_f32 v10, v7, v10, 0x43000000
	v_lshlrev_b32_e32 v12, 16, v13
	v_cvt_pk_u8_f32 v10, v10, 0, 0
	v_fmaak_f32 v11, v7, v11, 0x43000000
	v_and_b32_e32 v13, 0xffff0000, v13
	v_cvt_pk_u8_f32 v10, v11, 1, v10
	v_fmaak_f32 v11, v7, v12, 0x43000000
	v_cvt_pk_u8_f32 v10, v11, 2, v10
	v_fmaak_f32 v11, v7, v13, 0x43000000
	v_cvt_pk_u8_f32 v10, v11, 3, v10
	v_lshlrev_b32_e32 v11, 16, v14
	v_and_b32_e32 v12, 0xffff0000, v14
	v_fmaak_f32 v11, v7, v11, 0x43000000
	v_lshlrev_b32_e32 v13, 16, v15
	v_cvt_pk_u8_f32 v11, v11, 0, 0
	v_fmaak_f32 v12, v7, v12, 0x43000000
	v_and_b32_e32 v14, 0xffff0000, v15
	v_cvt_pk_u8_f32 v11, v12, 1, v11
	v_fmaak_f32 v12, v7, v13, 0x43000000
	v_xor_b32_e32 v8, 0x80808080, v8
	v_xor_b32_e32 v9, 0x80808080, v9
	v_cvt_pk_u8_f32 v11, v12, 2, v11
	v_fmaak_f32 v7, v7, v14, 0x43000000
	v_lshl_add_u64 v[12:13], s[4:5], 0, v[4:5]
	v_cvt_pk_u8_f32 v7, v7, 3, v11
	global_store_dwordx2 v[12:13], v[8:9], off
	v_lshl_add_u64 v[8:9], s[4:5], 0, v[2:3]
	v_xor_b32_e32 v10, 0x80808080, v10
	v_xor_b32_e32 v11, 0x80808080, v7
	global_store_dwordx2 v[8:9], v[10:11], off
	s_add_i32 s0, s0, 8
	s_ashr_i32 s4, s0, 4
	s_mul_hi_i32 s5, s4, 0x2e8ba2e9
	s_lshr_b32 s7, s5, 31
	s_ashr_i32 s5, s5, 1
	s_add_i32 s7, s5, s7
	s_mul_i32 s5, s7, 11
	s_sub_i32 s4, s4, s5
	s_mul_i32 s5, s66, 11
	s_add_i32 s8, s4, s5
	s_lshl_b32 s11, s8, 1
	s_add_i32 s10, s7, s13
	s_or_b32 s11, s11, s3
	s_and_b32 s6, s0, 15
	s_bfe_u32 s9, s0, 0x30001
	s_waitcnt vmcnt(20)
	v_mov_b32_e32 v8, v144
	v_mov_b32_e32 v9, v145
	v_mov_b32_e32 v10, v146
	v_mov_b32_e32 v11, v147
	v_mov_b32_e32 v12, v148
	v_mov_b32_e32 v13, v149
	v_mov_b32_e32 v14, v150
	v_mov_b32_e32 v15, v151
	s_mul_hi_i32 s5, s10, 44
	s_mul_i32 s10, s10, 44
	s_ashr_i32 s11, s8, 31
	s_add_u32 s4, s10, s8
	s_addc_u32 s5, s5, s11
	s_lshl_b64 s[4:5], s[4:5], 14
	s_add_u32 s4, s1, s4
	s_addc_u32 s5, s2, s5
	s_lshl_b32 s6, s6, 10
	s_add_u32 s4, s4, s6
	s_addc_u32 s5, s5, 0
	s_lshl_b32 s6, s7, 9
	s_add_i32 s6, s40, s6
	s_lshl_b32 s7, s9, 6
	s_add_i32 s6, s6, s7
	v_lshl_add_u32 v7, v6, 2, s6
	ds_read_b32 v7, v7
	v_lshlrev_b32_e32 v16, 16, v8
	v_and_b32_e32 v8, 0xffff0000, v8
	s_waitcnt lgkmcnt(0)
	v_fmaak_f32 v16, v7, v16, 0x43000000
	v_lshlrev_b32_e32 v17, 16, v9
	v_cvt_pk_u8_f32 v16, v16, 0, 0
	v_fmaak_f32 v8, v7, v8, 0x43000000
	v_and_b32_e32 v9, 0xffff0000, v9
	v_cvt_pk_u8_f32 v8, v8, 1, v16
	v_fmaak_f32 v16, v7, v17, 0x43000000
	v_cvt_pk_u8_f32 v8, v16, 2, v8
	v_fmaak_f32 v9, v7, v9, 0x43000000
	v_cvt_pk_u8_f32 v8, v9, 3, v8
	v_lshlrev_b32_e32 v9, 16, v10
	v_and_b32_e32 v10, 0xffff0000, v10
	v_fmaak_f32 v9, v7, v9, 0x43000000
	v_lshlrev_b32_e32 v16, 16, v11
	v_cvt_pk_u8_f32 v9, v9, 0, 0
	v_fmaak_f32 v10, v7, v10, 0x43000000
	v_and_b32_e32 v11, 0xffff0000, v11
	v_cvt_pk_u8_f32 v9, v10, 1, v9
	v_fmaak_f32 v10, v7, v16, 0x43000000
	v_cvt_pk_u8_f32 v9, v10, 2, v9
	v_fmaak_f32 v10, v7, v11, 0x43000000
	v_cvt_pk_u8_f32 v9, v10, 3, v9
	v_lshlrev_b32_e32 v10, 16, v12
	v_and_b32_e32 v11, 0xffff0000, v12
	v_fmaak_f32 v10, v7, v10, 0x43000000
	v_lshlrev_b32_e32 v12, 16, v13
	v_cvt_pk_u8_f32 v10, v10, 0, 0
	v_fmaak_f32 v11, v7, v11, 0x43000000
	v_and_b32_e32 v13, 0xffff0000, v13
	v_cvt_pk_u8_f32 v10, v11, 1, v10
	v_fmaak_f32 v11, v7, v12, 0x43000000
	v_cvt_pk_u8_f32 v10, v11, 2, v10
	v_fmaak_f32 v11, v7, v13, 0x43000000
	v_cvt_pk_u8_f32 v10, v11, 3, v10
	v_lshlrev_b32_e32 v11, 16, v14
	v_and_b32_e32 v12, 0xffff0000, v14
	v_fmaak_f32 v11, v7, v11, 0x43000000
	v_lshlrev_b32_e32 v13, 16, v15
	v_cvt_pk_u8_f32 v11, v11, 0, 0
	v_fmaak_f32 v12, v7, v12, 0x43000000
	v_and_b32_e32 v14, 0xffff0000, v15
	v_cvt_pk_u8_f32 v11, v12, 1, v11
	v_fmaak_f32 v12, v7, v13, 0x43000000
	v_xor_b32_e32 v8, 0x80808080, v8
	v_xor_b32_e32 v9, 0x80808080, v9
	v_cvt_pk_u8_f32 v11, v12, 2, v11
	v_fmaak_f32 v7, v7, v14, 0x43000000
	v_lshl_add_u64 v[12:13], s[4:5], 0, v[4:5]
	v_cvt_pk_u8_f32 v7, v7, 3, v11
	global_store_dwordx2 v[12:13], v[8:9], off
	v_lshl_add_u64 v[8:9], s[4:5], 0, v[2:3]
	v_xor_b32_e32 v10, 0x80808080, v10
	v_xor_b32_e32 v11, 0x80808080, v7
	global_store_dwordx2 v[8:9], v[10:11], off
	s_add_i32 s0, s0, 8
	s_cmpk_lt_i32 s0, 0x160
	s_cbranch_scc1 .LBB0_573
